# v18 + rg_item<3> conv stage: the 35 serial ds_read_u16 -> wait -> use x_r reads hoisted into fresh registers (one LDS latency instead of 35)
# speedup vs baseline: 1.0036x; 1.0036x over previous
.LBB0_819:
	s_ashr_i32 s13, s51, 6
	s_mul_i32 s0, s13, 0x1200
	s_add_i32 s4, s0, 0
	s_add_i32 s4, s4, 0x18c00
	s_add_u32 s0, s62, s54
	s_addc_u32 s1, s63, s55
	s_load_dwordx4 s[40:43], s[64:65], 0x50
	s_add_u32 s0, s0, 0x4000
	s_addc_u32 s1, s1, 0
	s_add_u32 s38, s38, s60
	s_addc_u32 s39, s39, s61
	s_waitcnt lgkmcnt(0)
	s_add_u32 s40, s40, s60
	s_addc_u32 s41, s41, s61
	v_lshl_add_u64 v[6:7], v[0:1], 2, s[40:41]
	v_add_co_u32_e32 v6, vcc, s3, v6
	v_add_u32_e32 v10, s58, v0
	v_mov_b32_e32 v2, s42
	v_mov_b32_e32 v3, s43
	v_lshl_add_u64 v[4:5], v[0:1], 2, s[40:41]
	v_addc_co_u32_e32 v7, vcc, 0, v7, vcc
	v_ashrrev_i32_e32 v11, 31, v10
	v_add_co_u32_e32 v8, vcc, s3, v4
	v_lshl_add_u64 v[2:3], v[10:11], 2, v[2:3]
	s_nop 0
	v_addc_co_u32_e32 v9, vcc, 0, v5, vcc
	global_load_dword v114, v[2:3], off
	global_load_dword v122, v[4:5], off
	global_load_dword v123, v[4:5], off offset:2048
	global_load_dword v124, v[6:7], off
	global_load_dword v125, v[8:9], off offset:2048
	v_lshl_add_u32 v0, v0, 1, 0
	s_barrier
	ds_read_u16 v182, v0
	ds_read_u16 v183, v0 offset:1024
	ds_read_u16 v184, v0 offset:2048
	ds_read_u16 v185, v0 offset:3072
	ds_read_u16 v186, v0 offset:4096
	ds_read_u16 v187, v0 offset:5120
	ds_read_u16 v188, v0 offset:6144
	ds_read_u16 v189, v0 offset:7168
	ds_read_u16 v190, v0 offset:8192
	ds_read_u16 v191, v0 offset:9216
	ds_read_u16 v192, v0 offset:10240
	ds_read_u16 v193, v0 offset:11264
	ds_read_u16 v194, v0 offset:12288
	ds_read_u16 v195, v0 offset:13312
	ds_read_u16 v196, v0 offset:14336
	ds_read_u16 v197, v0 offset:15360
	ds_read_u16 v198, v0 offset:16384
	ds_read_u16 v199, v0 offset:17408
	ds_read_u16 v200, v0 offset:18432
	ds_read_u16 v201, v0 offset:19456
	ds_read_u16 v202, v0 offset:20480
	ds_read_u16 v203, v0 offset:21504
	ds_read_u16 v214, v0 offset:22528
	ds_read_u16 v215, v0 offset:23552
	ds_read_u16 v216, v0 offset:24576
	ds_read_u16 v217, v0 offset:25600
	ds_read_u16 v218, v0 offset:26624
	ds_read_u16 v219, v0 offset:27648
	ds_read_u16 v220, v0 offset:28672
	ds_read_u16 v221, v0 offset:29696
	ds_read_u16 v222, v0 offset:30720
	ds_read_u16 v223, v0 offset:31744
	ds_read_u16 v224, v0 offset:32768
	ds_read_u16 v225, v0 offset:33792
	ds_read_u16 v226, v0 offset:34816
	s_waitcnt lgkmcnt(0)
	v_lshl_add_u32 v17, v112, 1, s4
	v_lshlrev_b32_e32 v1, 16, v182
	v_lshlrev_b32_e32 v5, 16, v183
	v_lshlrev_b32_e32 v6, 16, v184
	v_lshlrev_b32_e32 v7, 16, v185
	v_and_b32_e32 v172, 48, v112
	v_lshl_add_u64 v[2:3], s[62:63], 0, v[172:173]
	s_mov_b64 s[40:41], 0x3f2000
	v_lshl_add_u64 v[116:117], v[2:3], 0, s[40:41]
	v_and_b32_e32 v16, 15, v36
	s_add_i32 s29, s28, 0x600
	v_or_b32_e32 v4, s28, v16
	s_add_i32 s5, s28, 0x200
	s_add_i32 s26, s28, 0x400
	v_add_u32_e32 v126, s28, v16
	v_and_b32_e32 v127, 64, v212
	s_mov_b32 s35, 0
	s_waitcnt vmcnt(3)
	v_fma_f32 v1, v122, v1, v114
	s_waitcnt vmcnt(2)
	v_fmac_f32_e32 v1, v123, v5
	s_waitcnt vmcnt(1)
	v_fmac_f32_e32 v1, v124, v6
	s_waitcnt vmcnt(0)
	v_fmac_f32_e32 v1, v125, v7
	v_bfe_u32 v8, v1, 16, 1
	v_add3_u32 v1, v1, v8, s33
	ds_write_b16_d16_hi v17, v1
	v_fma_f32 v2, v122, v5, v114
	v_fmac_f32_e32 v2, v123, v6
	v_fmac_f32_e32 v2, v124, v7
	v_fma_f32 v5, v122, v6, v114
	v_lshlrev_b32_e32 v1, 16, v186
	v_fmac_f32_e32 v2, v125, v1
	v_bfe_u32 v3, v2, 16, 1
	v_add3_u32 v2, v2, v3, s33
	ds_write_b16_d16_hi v17, v2 offset:144
	v_fmac_f32_e32 v5, v123, v7
	v_fmac_f32_e32 v5, v124, v1
	v_fma_f32 v7, v122, v7, v114
	v_fmac_f32_e32 v7, v123, v1
	v_lshlrev_b32_e32 v3, 16, v187
	v_fmac_f32_e32 v5, v125, v3
	v_bfe_u32 v6, v5, 16, 1
	v_add3_u32 v5, v5, v6, s33
	ds_write_b16_d16_hi v17, v5 offset:288
	v_fmac_f32_e32 v7, v124, v3
	v_fma_f32 v1, v122, v1, v114
	v_fmac_f32_e32 v1, v123, v3
	v_fma_f32 v3, v122, v3, v114
	v_lshlrev_b32_e32 v9, 16, v188
	v_fmac_f32_e32 v7, v125, v9
	v_bfe_u32 v6, v7, 16, 1
	v_add3_u32 v6, v7, v6, s33
	ds_write_b16_d16_hi v17, v6 offset:432
	v_fmac_f32_e32 v1, v124, v9
	v_fmac_f32_e32 v3, v123, v9
	v_fma_f32 v9, v122, v9, v114
	v_ashrrev_i32_e32 v5, 31, v4
	v_lshlrev_b32_e32 v7, 16, v189
	v_fmac_f32_e32 v1, v125, v7
	v_bfe_u32 v8, v1, 16, 1
	v_add3_u32 v1, v1, v8, s33
	ds_write_b16_d16_hi v17, v1 offset:576
	v_fmac_f32_e32 v3, v124, v7
	v_fmac_f32_e32 v9, v123, v7
	v_fma_f32 v7, v122, v7, v114
	v_add_u32_e32 v2, 0x200, v126
	v_lshlrev_b32_e32 v1, 16, v190
	v_fmac_f32_e32 v3, v125, v1
	v_bfe_u32 v10, v3, 16, 1
	v_add3_u32 v3, v3, v10, s33
	ds_write_b16_d16_hi v17, v3 offset:720
	v_fmac_f32_e32 v9, v124, v1
	v_fmac_f32_e32 v7, v123, v1
	v_fma_f32 v1, v122, v1, v114
	v_add_u32_e32 v6, 0x400, v4
	v_lshlrev_b32_e32 v12, 16, v191
	v_fmac_f32_e32 v9, v125, v12
	v_bfe_u32 v3, v9, 16, 1
	v_add3_u32 v3, v9, v3, s33
	ds_write_b16_d16_hi v17, v3 offset:864
	v_fmac_f32_e32 v7, v124, v12
	v_fmac_f32_e32 v1, v123, v12
	v_fma_f32 v9, v122, v12, v114
	v_add_u32_e32 v8, 0x600, v126
	v_lshlrev_b32_e32 v13, 16, v192
	v_fmac_f32_e32 v7, v125, v13
	v_bfe_u32 v3, v7, 16, 1
	v_add3_u32 v3, v7, v3, s33
	ds_write_b16_d16_hi v17, v3 offset:1008
	v_fmac_f32_e32 v1, v124, v13
	v_fmac_f32_e32 v9, v123, v13
	v_fma_f32 v13, v122, v13, v114
	v_lshlrev_b64 v[10:11], 7, v[4:5]
	v_lshlrev_b32_e32 v14, 16, v193
	v_fmac_f32_e32 v1, v125, v14
	v_bfe_u32 v7, v1, 16, 1
	v_add3_u32 v1, v1, v7, s33
	ds_write_b16_d16_hi v17, v1 offset:1152
	v_fmac_f32_e32 v9, v124, v14
	v_fmac_f32_e32 v13, v123, v14
	v_lshlrev_b64 v[4:5], 2, v[4:5]
	v_ashrrev_i32_e32 v3, 31, v2
	v_lshlrev_b32_e32 v1, 16, v194
	v_fmac_f32_e32 v9, v125, v1
	v_bfe_u32 v12, v9, 16, 1
	v_add3_u32 v9, v9, v12, s33
	ds_write_b16_d16_hi v17, v9 offset:1296
	v_fmac_f32_e32 v13, v124, v1
	v_ashrrev_i32_e32 v7, 31, v6
	v_ashrrev_i32_e32 v9, 31, v8
	v_lshl_add_u64 v[10:11], v[116:117], 0, v[10:11]
	v_lshlrev_b32_e32 v15, 16, v195
	v_fmac_f32_e32 v13, v125, v15
	v_bfe_u32 v12, v13, 16, 1
	v_add3_u32 v12, v13, v12, s33
	ds_write_b16_d16_hi v17, v12 offset:1440
	v_fma_f32 v13, v122, v14, v114
	v_fmac_f32_e32 v13, v123, v1
	v_fmac_f32_e32 v13, v124, v15
	v_fma_f32 v1, v122, v1, v114
	v_lshlrev_b32_e32 v14, 16, v196
	v_fmac_f32_e32 v13, v125, v14
	v_bfe_u32 v12, v13, 16, 1
	v_add3_u32 v12, v13, v12, s33
	ds_write_b16_d16_hi v17, v12 offset:1584
	v_fmac_f32_e32 v1, v123, v15
	v_fmac_f32_e32 v1, v124, v14
	v_fma_f32 v15, v122, v15, v114
	v_fmac_f32_e32 v15, v123, v14
	v_lshlrev_b32_e32 v18, 16, v197
	v_fmac_f32_e32 v1, v125, v18
	v_bfe_u32 v19, v1, 16, 1
	v_add3_u32 v1, v1, v19, s33
	ds_write_b16_d16_hi v17, v1 offset:1728
	v_fmac_f32_e32 v15, v124, v18
	v_fma_f32 v14, v122, v14, v114
	v_fmac_f32_e32 v14, v123, v18
	v_fma_f32 v18, v122, v18, v114
	v_lshlrev_b32_e32 v1, 16, v198
	v_fmac_f32_e32 v15, v125, v1
	v_bfe_u32 v19, v15, 16, 1
	v_add3_u32 v15, v15, v19, s33
	ds_write_b16_d16_hi v17, v15 offset:1872
	v_fmac_f32_e32 v14, v124, v1
	v_fmac_f32_e32 v18, v123, v1
	v_fma_f32 v1, v122, v1, v114
	v_lshl_add_u64 v[12:13], s[0:1], 0, v[4:5]
	v_lshlrev_b32_e32 v15, 16, v199
	v_fmac_f32_e32 v14, v125, v15
	v_bfe_u32 v19, v14, 16, 1
	v_add3_u32 v14, v14, v19, s33
	ds_write_b16_d16_hi v17, v14 offset:2016
	v_fmac_f32_e32 v18, v124, v15
	v_fmac_f32_e32 v1, v123, v15
	v_fma_f32 v15, v122, v15, v114
	v_lshl_add_u64 v[4:5], s[38:39], 0, v[4:5]
	v_lshlrev_b32_e32 v14, 16, v200
	v_fmac_f32_e32 v18, v125, v14
	v_bfe_u32 v19, v18, 16, 1
	v_add3_u32 v18, v18, v19, s33
	ds_write_b16_d16_hi v17, v18 offset:2160
	v_fmac_f32_e32 v1, v124, v14
	v_fmac_f32_e32 v15, v123, v14
	v_fma_f32 v14, v122, v14, v114
	v_lshl_add_u64 v[2:3], v[2:3], 2, s[38:39]
	v_lshlrev_b32_e32 v18, 16, v201
	v_fmac_f32_e32 v1, v125, v18
	v_bfe_u32 v19, v1, 16, 1
	v_add3_u32 v1, v1, v19, s33
	ds_write_b16_d16_hi v17, v1 offset:2304
	v_fmac_f32_e32 v15, v124, v18
	v_fmac_f32_e32 v14, v123, v18
	v_fma_f32 v18, v122, v18, v114
	v_lshl_add_u64 v[6:7], v[6:7], 2, s[38:39]
	v_lshlrev_b32_e32 v1, 16, v202
	v_fmac_f32_e32 v15, v125, v1
	v_bfe_u32 v19, v15, 16, 1
	v_add3_u32 v15, v15, v19, s33
	ds_write_b16_d16_hi v17, v15 offset:2448
	v_fmac_f32_e32 v14, v124, v1
	v_fmac_f32_e32 v18, v123, v1
	v_fma_f32 v1, v122, v1, v114
	v_lshl_add_u64 v[8:9], v[8:9], 2, s[38:39]
	v_lshlrev_b32_e32 v15, 16, v203
	v_fmac_f32_e32 v14, v125, v15
	v_bfe_u32 v19, v14, 16, 1
	v_add3_u32 v14, v14, v19, s33
	ds_write_b16_d16_hi v17, v14 offset:2592
	v_fmac_f32_e32 v18, v124, v15
	v_fmac_f32_e32 v1, v123, v15
	v_fma_f32 v15, v122, v15, v114
	v_lshlrev_b32_e32 v19, 16, v214
	v_fmac_f32_e32 v18, v125, v19
	v_bfe_u32 v14, v18, 16, 1
	v_add3_u32 v14, v18, v14, s33
	ds_write_b16_d16_hi v17, v14 offset:2736
	v_fmac_f32_e32 v1, v124, v19
	v_fmac_f32_e32 v15, v123, v19
	v_fma_f32 v19, v122, v19, v114
	v_or_b32_e32 v14, s5, v16
	v_lshlrev_b32_e32 v21, 16, v215
	v_fmac_f32_e32 v1, v125, v21
	v_bfe_u32 v18, v1, 16, 1
	v_add3_u32 v1, v1, v18, s33
	ds_write_b16_d16_hi v17, v1 offset:2880
	v_fmac_f32_e32 v15, v124, v21
	v_fmac_f32_e32 v19, v123, v21
	v_fma_f32 v21, v122, v21, v114
	v_or_b32_e32 v18, s26, v16
	v_lshlrev_b32_e32 v1, 16, v216
	v_fmac_f32_e32 v15, v125, v1
	v_bfe_u32 v20, v15, 16, 1
	v_add3_u32 v15, v15, v20, s33
	ds_write_b16_d16_hi v17, v15 offset:3024
	v_fmac_f32_e32 v19, v124, v1
	v_fmac_f32_e32 v21, v123, v1
	v_fma_f32 v1, v122, v1, v114
	v_or_b32_e32 v20, s29, v16
	v_lshlrev_b32_e32 v22, 16, v217
	v_fmac_f32_e32 v19, v125, v22
	v_bfe_u32 v15, v19, 16, 1
	v_add3_u32 v15, v19, v15, s33
	ds_write_b16_d16_hi v17, v15 offset:3168
	v_fmac_f32_e32 v21, v124, v22
	v_fmac_f32_e32 v1, v123, v22
	v_fma_f32 v22, v122, v22, v114
	v_ashrrev_i32_e32 v15, 31, v14
	v_lshlrev_b32_e32 v23, 16, v218
	v_fmac_f32_e32 v21, v125, v23
	v_bfe_u32 v19, v21, 16, 1
	v_add3_u32 v19, v21, v19, s33
	ds_write_b16_d16_hi v17, v19 offset:3312
	v_fmac_f32_e32 v1, v124, v23
	v_fmac_f32_e32 v22, v123, v23
	v_fma_f32 v23, v122, v23, v114
	v_ashrrev_i32_e32 v19, 31, v18
	v_lshlrev_b32_e32 v24, 16, v219
	v_fmac_f32_e32 v1, v125, v24
	v_bfe_u32 v21, v1, 16, 1
	v_add3_u32 v1, v1, v21, s33
	ds_write_b16_d16_hi v17, v1 offset:3456
	v_fmac_f32_e32 v22, v124, v24
	v_fmac_f32_e32 v23, v123, v24
	v_fma_f32 v24, v122, v24, v114
	v_ashrrev_i32_e32 v21, 31, v20
	v_lshlrev_b32_e32 v1, 16, v220
	v_fmac_f32_e32 v22, v125, v1
	v_bfe_u32 v25, v22, 16, 1
	v_add3_u32 v22, v22, v25, s33
	ds_write_b16_d16_hi v17, v22 offset:3600
	v_fmac_f32_e32 v23, v124, v1
	v_fmac_f32_e32 v24, v123, v1
	v_fma_f32 v1, v122, v1, v114
	v_lshlrev_b64 v[20:21], 7, v[20:21]
	v_lshlrev_b32_e32 v22, 16, v221
	v_fmac_f32_e32 v23, v125, v22
	v_bfe_u32 v25, v23, 16, 1
	v_add3_u32 v23, v23, v25, s33
	ds_write_b16_d16_hi v17, v23 offset:3744
	v_fmac_f32_e32 v24, v124, v22
	v_fmac_f32_e32 v1, v123, v22
	v_fma_f32 v22, v122, v22, v114
	v_lshlrev_b64 v[14:15], 7, v[14:15]
	v_lshlrev_b32_e32 v23, 16, v222
	v_fmac_f32_e32 v24, v125, v23
	v_bfe_u32 v25, v24, 16, 1
	v_add3_u32 v24, v24, v25, s33
	ds_write_b16_d16_hi v17, v24 offset:3888
	v_fmac_f32_e32 v1, v124, v23
	v_fmac_f32_e32 v22, v123, v23
	v_lshlrev_b64 v[18:19], 7, v[18:19]
	v_lshl_add_u64 v[14:15], v[116:117], 0, v[14:15]
	v_lshlrev_b32_e32 v24, 16, v223
	v_fmac_f32_e32 v1, v125, v24
	v_bfe_u32 v25, v1, 16, 1
	v_add3_u32 v1, v1, v25, s33
	ds_write_b16_d16_hi v17, v1 offset:4032
	v_fmac_f32_e32 v22, v124, v24
	v_lshl_add_u64 v[18:19], v[116:117], 0, v[18:19]
	s_lshl_b32 s26, s57, 1
	s_and_b32 s26, s26, 62
	v_lshlrev_b32_e32 v25, 16, v224
	v_fmac_f32_e32 v22, v125, v25
	v_bfe_u32 v1, v22, 16, 1
	v_add3_u32 v1, v22, v1, s33
	ds_write_b16_d16_hi v17, v1 offset:4176
	v_fma_f32 v22, v122, v23, v114
	v_fmac_f32_e32 v22, v123, v24
	v_fmac_f32_e32 v22, v124, v25
	s_or_b32 s26, s26, s50
	v_lshlrev_b32_e32 v23, 16, v225
	v_fmac_f32_e32 v22, v125, v23
	v_bfe_u32 v1, v22, 16, 1
	v_add3_u32 v1, v22, v1, s33
	ds_write_b16_d16_hi v17, v1 offset:4320
	v_lshl_add_u64 v[0:1], v[116:117], 0, v[20:21]
	v_fma_f32 v20, v122, v24, v114
	v_fmac_f32_e32 v20, v123, v25
	v_fmac_f32_e32 v20, v124, v23
	v_lshlrev_b32_e32 v21, 16, v226
	v_fmac_f32_e32 v20, v125, v21
	v_bfe_u32 v21, v20, 16, 1
	v_add3_u32 v20, v20, v21, s33
	ds_write_b16_d16_hi v17, v20 offset:4464
	s_waitcnt lgkmcnt(0)
	global_load_dwordx4 v[64:67], v[10:11], off
	global_load_dwordx4 v[72:75], v[10:11], off offset:64
	global_load_dwordx4 v[68:71], v[14:15], off
	global_load_dwordx4 v[76:79], v[14:15], off offset:64
	global_load_dword v96, v[4:5], off
	global_load_dword v95, v[2:3], off
	global_load_dwordx4 v[56:59], v[18:19], off offset:64
	global_load_dwordx4 v[52:55], v[0:1], off
	global_load_dwordx4 v[60:63], v[0:1], off offset:64
	global_load_dword v89, v[6:7], off
	global_load_dword v88, v[8:9], off
	global_load_dword v94, v[12:13], off
	global_load_dwordx4 v[48:51], v[18:19], off
	global_load_dword v87, v[12:13], off offset:2048
	v_and_b32_e32 v0, 48, v36
	v_mul_u32_u24_e32 v1, 0x90, v16
	v_add3_u32 v12, s4, v0, v1
	ds_read_b128 v[0:3], v12
	ds_read_b128 v[4:7], v12 offset:64
	ds_read_b128 v[8:11], v12 offset:2304
	ds_read_b128 v[12:15], v12 offset:2368
	s_load_dwordx2 s[4:5], s[64:65], 0x100
	s_lshl_b32 s26, s26, 10
	s_lshl_b64 s[40:41], s[26:27], 2
	v_lshrrev_b32_e32 v17, 4, v112
	v_xor_b32_e32 v18, 2, v17
	s_waitcnt lgkmcnt(0)
	s_add_u32 s26, s4, s40
	s_addc_u32 s29, s5, s41
	s_add_u32 s48, s26, 0x6000000
	s_addc_u32 s49, s29, 0
	s_cmp_lt_i32 s57, 32
	s_cselect_b64 s[46:47], -1, 0
	s_and_b64 s[46:47], s[44:45], s[46:47]
	v_cmp_gt_u32_e64 s[44:45], 16, v112
	s_and_b64 s[66:67], s[46:47], s[44:45]
	s_cmp_lg_u32 s71, s70
	s_cselect_b64 s[70:71], -1, 0
	s_lshl_b32 s26, s51, 1
	v_add_u32_e32 v19, 16, v36
	s_and_b32 s26, s26, 0xffffff80
	v_and_or_b32 v19, v19, 63, v127
	v_cmp_eq_u32_e64 s[40:41], 3, v17
	v_cmp_lt_u32_e64 s[42:43], 1, v18
	v_or_b32_e32 v18, v127, v16
	v_cmp_ne_u32_e32 vcc, 3, v17
	v_lshl_add_u32 v17, v17, 12, s26
	s_and_b32 s26, s57, 31
	v_lshlrev_b32_e32 v128, 2, v19
	v_or_b32_e32 v19, v127, v112
	v_lshlrev_b32_e32 v130, 2, v18
	v_add_u32_e32 v18, 48, v36
	s_lshl_b32 s26, s26, 11
	v_lshlrev_b32_e32 v19, 2, v19
	v_and_or_b32 v18, v18, 63, v127
	s_or_b64 s[70:71], vcc, s[70:71]
	s_ashr_i32 s29, s28, 31
	v_lshl_or_b32 v133, v16, 1, v17
	v_mov_b32_e32 v17, v173
	s_add_i32 s26, s56, s26
	v_xor_b32_e32 v129, 0x80, v19
	v_lshlrev_b32_e32 v131, 2, v18
	v_or_b32_e32 v132, 0xc0, v19
	s_nor_b64 s[68:69], s[70:71], s[68:69]
	v_lshl_add_u64 v[18:19], s[28:29], 0, v[16:17]
	s_lshl_b64 s[28:29], s[26:27], 2
	s_add_u32 s4, s4, s28
	s_addc_u32 s5, s5, s29
	v_lshl_add_u64 v[118:119], v[18:19], 2, s[4:5]
	v_lshlrev_b32_e32 v17, 2, v212
	v_lshlrev_b32_e32 v16, 2, v16
	s_movk_i32 s4, 0x100
	v_cmp_lt_u32_e64 s[46:47], 31, v112
	v_and_or_b32 v172, v17, s4, v16
	s_mov_b64 s[70:71], 0
	s_mov_b32 s26, 0
	v_readlane_b32 s51, v240, 36
	s_branch .LBB0_821
